# peer_q top-k pair stage: 50 candidate insertions replaced by three 16-input sorts + two bitonic prune-merges + two insertions (same keys, same sorted list)
# baseline (speedup 1.0000x reference)
; DI void phase_peer_q(const Params& p, int layer, u16* lds, const int WAVE_S) {
;     ...
;     float c[16];
; #pragma unroll
;     for (int i = 0; i < 16; ++i) c[i] = -3.0e38f;
; #pragma unroll
;     for (int i = 0; i < 16; ++i)
; #pragma unroll
;       for (int j = 0; j < 16; ++j)
;         if ((i + 1) * (j + 1) <= 16) {
;           const float sv = t0[i] + t[j];
;           ins16(c, __uint_as_float((__float_as_uint(sv) & ~255u) | (uint32_t)(i * 16 + j)));
;         }
.LBB0_396:
	s_or_b64 exec, exec, s[18:19]
	v_add_f32_e32 v18, v2, v98
	v_and_b32_e32 v18, 0xffffff00, v18
	v_add_f32_e32 v19, v3, v98
	v_and_or_b32 v19, v19, s93, 1
	v_add_f32_e32 v20, v4, v98
	v_and_or_b32 v20, v20, s93, 2
	v_add_f32_e32 v21, v5, v98
	v_and_or_b32 v21, v21, s93, 3
	v_add_f32_e32 v22, v6, v98
	v_and_or_b32 v22, v22, s93, 4
	v_add_f32_e32 v23, v7, v98
	v_and_or_b32 v23, v23, s93, 5
	v_add_f32_e32 v24, v8, v98
	v_and_or_b32 v24, v24, s93, 6
	v_add_f32_e32 v25, v9, v98
	v_and_or_b32 v25, v25, s93, 7
	v_add_f32_e32 v26, v16, v98
	v_and_or_b32 v26, v26, s93, 8
	v_add_f32_e32 v27, v17, v98
	v_and_or_b32 v27, v27, s93, 9
	v_add_f32_e32 v28, v14, v98
	v_and_or_b32 v28, v28, s93, 10
	v_add_f32_e32 v29, v15, v98
	v_and_or_b32 v29, v29, s93, 11
	v_add_f32_e32 v134, v12, v98
	v_and_or_b32 v134, v134, s93, 12
	v_add_f32_e32 v135, v13, v98
	v_and_or_b32 v135, v135, s93, 13
	v_add_f32_e32 v136, v10, v98
	v_and_or_b32 v136, v136, s93, 14
	v_add_f32_e32 v137, v11, v98
	v_and_or_b32 v137, v137, s93, 15
	v_add_f32_e32 v138, v2, v99
	v_and_or_b32 v138, v138, s93, 16
	v_add_f32_e32 v139, v3, v99
	v_and_or_b32 v139, v139, s93, 17
	v_add_f32_e32 v140, v4, v99
	v_and_or_b32 v140, v140, s93, 18
	v_add_f32_e32 v141, v5, v99
	v_and_or_b32 v141, v141, s93, 19
	v_add_f32_e32 v142, v6, v99
	v_and_or_b32 v142, v142, s93, 20
	v_add_f32_e32 v143, v7, v99
	v_and_or_b32 v143, v143, s93, 21
	v_add_f32_e32 v144, v8, v99
	v_and_or_b32 v144, v144, s93, 22
	v_add_f32_e32 v145, v9, v99
	v_and_or_b32 v145, v145, s93, 23
	v_add_f32_e32 v148, v2, v100
	v_and_or_b32 v148, v148, s93, 32
	v_add_f32_e32 v149, v3, v100
	v_and_or_b32 v149, v149, s93, 33
	v_add_f32_e32 v150, v4, v100
	v_and_or_b32 v150, v150, s93, 34
	v_add_f32_e32 v151, v5, v100
	v_and_or_b32 v151, v151, s93, 35
	v_add_f32_e32 v152, v6, v100
	v_and_or_b32 v152, v152, s93, 36
	v_add_f32_e32 v153, v2, v101
	v_and_or_b32 v153, v153, s93, 48
	v_add_f32_e32 v154, v3, v101
	v_and_or_b32 v154, v154, s93, 49
	v_add_f32_e32 v155, v4, v101
	v_and_or_b32 v155, v155, s93, 50
	v_add_f32_e32 v156, v5, v101
	v_and_or_b32 v156, v156, s93, 51
	v_add_f32_e32 v157, v2, v102
	v_and_or_b32 v157, v157, s93, 64
	v_add_f32_e32 v158, v3, v102
	v_and_b32_e32 v158, 0xffffff00, v158
	v_or_b32_e32 v158, 0x41, v158
	v_add_f32_e32 v159, v4, v102
	v_and_b32_e32 v159, 0xffffff00, v159
	v_or_b32_e32 v159, 0x42, v159
	v_add_f32_e32 v160, v2, v103
	v_and_b32_e32 v160, 0xffffff00, v160
	v_or_b32_e32 v160, 0x50, v160
	v_add_f32_e32 v161, v3, v103
	v_and_b32_e32 v161, 0xffffff00, v161
	v_or_b32_e32 v161, 0x51, v161
	v_add_f32_e32 v162, v2, v104
	v_and_b32_e32 v162, 0xffffff00, v162
	v_or_b32_e32 v162, 0x60, v162
	v_add_f32_e32 v163, v3, v104
	v_and_b32_e32 v163, 0xffffff00, v163
	v_or_b32_e32 v163, 0x61, v163
	v_add_f32_e32 v34, v2, v105
	v_and_b32_e32 v34, 0xffffff00, v34
	v_or_b32_e32 v34, 0x70, v34
	v_add_f32_e32 v35, v3, v105
	v_and_b32_e32 v35, 0xffffff00, v35
	v_or_b32_e32 v35, 0x71, v35
	v_add_f32_e32 v36, v2, v106
	v_and_b32_e32 v36, 0xffffff00, v36
	v_or_b32_e32 v36, 0x80, v36
	v_add_f32_e32 v37, v2, v107
	v_and_b32_e32 v37, 0xffffff00, v37
	v_or_b32_e32 v37, 0x90, v37
	v_add_f32_e32 v38, v2, v108
	v_and_b32_e32 v38, 0xffffff00, v38
	v_or_b32_e32 v38, 0xa0, v38
	v_add_f32_e32 v39, v2, v109
	v_and_b32_e32 v39, 0xffffff00, v39
	v_or_b32_e32 v39, 0xb0, v39
	v_add_f32_e32 v40, v2, v110
	v_and_b32_e32 v40, 0xffffff00, v40
	v_or_b32_e32 v40, 0xc0, v40
	v_add_f32_e32 v41, v2, v111
	v_and_b32_e32 v41, 0xffffff00, v41
	v_or_b32_e32 v41, 0xd0, v41
	v_add_f32_e32 v42, v2, v112
	v_and_b32_e32 v42, 0xffffff00, v42
	v_or_b32_e32 v42, 0xe0, v42
	v_add_f32_e32 v43, v2, v113
	v_and_b32_e32 v43, 0xffffff00, v43
	v_or_b32_e32 v43, 0xf0, v43
	v_min_f32_e32 v44, v18, v19
	v_max_f32_e32 v18, v18, v19
	v_min_f32_e32 v45, v20, v21
	v_max_f32_e32 v20, v20, v21
	v_min_f32_e32 v46, v18, v20
	v_max_f32_e32 v18, v18, v20
	v_min_f32_e32 v47, v44, v45
	v_max_f32_e32 v44, v44, v45
	v_min_f32_e32 v48, v44, v46
	v_max_f32_e32 v44, v44, v46
	v_min_f32_e32 v49, v22, v23
	v_max_f32_e32 v22, v22, v23
	v_min_f32_e32 v50, v24, v25
	v_max_f32_e32 v24, v24, v25
	v_min_f32_e32 v51, v22, v24
	v_max_f32_e32 v22, v22, v24
	v_min_f32_e32 v52, v49, v50
	v_max_f32_e32 v49, v49, v50
	v_min_f32_e32 v53, v49, v51
	v_max_f32_e32 v49, v49, v51
	v_min_f32_e32 v54, v18, v22
	v_max_f32_e32 v18, v18, v22
	v_min_f32_e32 v55, v48, v53
	v_max_f32_e32 v48, v48, v53
	v_min_f32_e32 v56, v48, v54
	v_max_f32_e32 v48, v48, v54
	v_min_f32_e32 v57, v44, v49
	v_max_f32_e32 v44, v44, v49
	v_min_f32_e32 v58, v47, v52
	v_max_f32_e32 v47, v47, v52
	v_min_f32_e32 v59, v47, v57
	v_max_f32_e32 v47, v47, v57
	v_min_f32_e32 v60, v44, v48
	v_max_f32_e32 v44, v44, v48
	v_min_f32_e32 v61, v47, v56
	v_max_f32_e32 v47, v47, v56
	v_min_f32_e32 v62, v59, v55
	v_max_f32_e32 v59, v59, v55
	v_min_f32_e32 v63, v26, v27
	v_max_f32_e32 v26, v26, v27
	v_min_f32_e32 v64, v28, v29
	v_max_f32_e32 v28, v28, v29
	v_min_f32_e32 v65, v26, v28
	v_max_f32_e32 v26, v26, v28
	v_min_f32_e32 v2, v63, v64
	v_max_f32_e32 v63, v63, v64
	v_min_f32_e32 v3, v63, v65
	v_max_f32_e32 v63, v63, v65
	v_min_f32_e32 v4, v134, v135
	v_max_f32_e32 v134, v134, v135
	v_min_f32_e32 v5, v136, v137
	v_max_f32_e32 v136, v136, v137
	v_min_f32_e32 v6, v134, v136
	v_max_f32_e32 v134, v134, v136
	v_min_f32_e32 v7, v4, v5
	v_max_f32_e32 v4, v4, v5
	v_min_f32_e32 v8, v4, v6
	v_max_f32_e32 v4, v4, v6
	v_min_f32_e32 v9, v26, v134
	v_max_f32_e32 v26, v26, v134
	v_min_f32_e32 v10, v3, v8
	v_max_f32_e32 v3, v3, v8
	v_min_f32_e32 v11, v3, v9
	v_max_f32_e32 v3, v3, v9
	v_min_f32_e32 v12, v63, v4
	v_max_f32_e32 v63, v63, v4
	v_min_f32_e32 v13, v2, v7
	v_max_f32_e32 v2, v2, v7
; DI void phase_peer_q(const Params& p, int layer, u16* lds, const int WAVE_S) {
;     ...
;     for (int i = 0; i < 16; ++i)
; #pragma unroll
;       for (int j = 0; j < 16; ++j)
;         if ((i + 1) * (j + 1) <= 16) {
;           const float sv = t0[i] + t[j];
;           ins16(c, __uint_as_float((__float_as_uint(sv) & ~255u) | (uint32_t)(i * 16 + j)));
;         }
	v_min_f32_e32 v14, v2, v12
	v_max_f32_e32 v2, v2, v12
	v_min_f32_e32 v15, v63, v3
	v_max_f32_e32 v63, v63, v3
	v_min_f32_e32 v16, v2, v11
	v_max_f32_e32 v2, v2, v11
	v_min_f32_e32 v17, v14, v10
	v_max_f32_e32 v14, v14, v10
	v_min_f32_e32 v19, v18, v26
	v_max_f32_e32 v18, v18, v26
	v_min_f32_e32 v21, v61, v16
	v_max_f32_e32 v61, v61, v16
	v_min_f32_e32 v20, v61, v19
	v_max_f32_e32 v61, v61, v19
	v_min_f32_e32 v45, v60, v15
	v_max_f32_e32 v60, v60, v15
	v_min_f32_e32 v46, v62, v17
	v_max_f32_e32 v62, v62, v17
	v_min_f32_e32 v23, v62, v45
	v_max_f32_e32 v62, v62, v45
	v_min_f32_e32 v25, v60, v61
	v_max_f32_e32 v60, v60, v61
	v_min_f32_e32 v24, v62, v20
	v_max_f32_e32 v62, v62, v20
	v_min_f32_e32 v50, v23, v21
	v_max_f32_e32 v23, v23, v21
	v_min_f32_e32 v51, v44, v63
	v_max_f32_e32 v44, v44, v63
	v_min_f32_e32 v22, v59, v14
	v_max_f32_e32 v59, v59, v14
	v_min_f32_e32 v53, v59, v51
	v_max_f32_e32 v59, v59, v51
	v_min_f32_e32 v54, v47, v2
	v_max_f32_e32 v47, v47, v2
	v_min_f32_e32 v49, v58, v13
	v_max_f32_e32 v58, v58, v13
	v_min_f32_e32 v52, v58, v54
	v_max_f32_e32 v58, v58, v54
	v_min_f32_e32 v57, v47, v59
	v_max_f32_e32 v47, v47, v59
	v_min_f32_e32 v48, v58, v53
	v_max_f32_e32 v58, v58, v53
	v_min_f32_e32 v56, v52, v22
	v_max_f32_e32 v52, v52, v22
	v_min_f32_e32 v55, v44, v60
	v_max_f32_e32 v44, v44, v60
	v_min_f32_e32 v27, v47, v25
	v_max_f32_e32 v47, v47, v25
	v_min_f32_e32 v29, v57, v62
	v_max_f32_e32 v57, v57, v62
	v_min_f32_e32 v28, v58, v24
	v_max_f32_e32 v58, v58, v24
	v_min_f32_e32 v64, v48, v23
	v_max_f32_e32 v48, v48, v23
	v_min_f32_e32 v65, v52, v50
	v_max_f32_e32 v52, v52, v50
	v_min_f32_e32 v135, v56, v46
	v_max_f32_e32 v56, v56, v46
	v_min_f32_e32 v137, v138, v139
	v_max_f32_e32 v138, v138, v139
	v_min_f32_e32 v136, v140, v141
	v_max_f32_e32 v140, v140, v141
	v_min_f32_e32 v5, v138, v140
	v_max_f32_e32 v138, v138, v140
	v_min_f32_e32 v6, v137, v136
	v_max_f32_e32 v137, v137, v136
	v_min_f32_e32 v134, v137, v5
	v_max_f32_e32 v137, v137, v5
	v_min_f32_e32 v8, v142, v143
	v_max_f32_e32 v142, v142, v143
	v_min_f32_e32 v9, v144, v145
	v_max_f32_e32 v144, v144, v145
	v_min_f32_e32 v4, v142, v144
	v_max_f32_e32 v142, v142, v144
	v_min_f32_e32 v7, v8, v9
	v_max_f32_e32 v8, v8, v9
	v_min_f32_e32 v12, v8, v4
	v_max_f32_e32 v8, v8, v4
	v_min_f32_e32 v3, v138, v142
	v_max_f32_e32 v138, v138, v142
	v_min_f32_e32 v11, v134, v12
	v_max_f32_e32 v134, v134, v12
	v_min_f32_e32 v10, v134, v3
	v_max_f32_e32 v134, v134, v3
	v_min_f32_e32 v26, v137, v8
	v_max_f32_e32 v137, v137, v8
	v_min_f32_e32 v16, v6, v7
	v_max_f32_e32 v6, v6, v7
	v_min_f32_e32 v19, v6, v26
	v_max_f32_e32 v6, v6, v26
	v_min_f32_e32 v15, v137, v134
	v_max_f32_e32 v137, v137, v134
	v_min_f32_e32 v17, v6, v10
	v_max_f32_e32 v6, v6, v10
	v_min_f32_e32 v45, v19, v11
	v_max_f32_e32 v19, v19, v11
	v_min_f32_e32 v61, v148, v149
	v_max_f32_e32 v148, v148, v149
	v_min_f32_e32 v20, v150, v151
	v_max_f32_e32 v150, v150, v151
	v_min_f32_e32 v21, v148, v150
	v_max_f32_e32 v148, v148, v150
	v_min_f32_e32 v63, v61, v20
	v_max_f32_e32 v61, v61, v20
	v_min_f32_e32 v14, v61, v21
	v_max_f32_e32 v61, v61, v21
	v_min_f32_e32 v51, v152, v153
	v_max_f32_e32 v152, v152, v153
	v_min_f32_e32 v2, v154, v155
	v_max_f32_e32 v154, v154, v155
	v_min_f32_e32 v13, v152, v154
	v_max_f32_e32 v152, v152, v154
	v_min_f32_e32 v54, v51, v2
	v_max_f32_e32 v51, v51, v2
	v_min_f32_e32 v59, v51, v13
	v_max_f32_e32 v51, v51, v13
	v_min_f32_e32 v53, v148, v152
	v_max_f32_e32 v148, v148, v152
	v_min_f32_e32 v22, v14, v59
	v_max_f32_e32 v14, v14, v59
	v_min_f32_e32 v60, v14, v53
	v_max_f32_e32 v14, v14, v53
	v_min_f32_e32 v25, v61, v51
	v_max_f32_e32 v61, v61, v51
	v_min_f32_e32 v62, v63, v54
	v_max_f32_e32 v63, v63, v54
	v_min_f32_e32 v24, v63, v25
	v_max_f32_e32 v63, v63, v25
	v_min_f32_e32 v23, v61, v14
	v_max_f32_e32 v61, v61, v14
	v_min_f32_e32 v50, v63, v60
	v_max_f32_e32 v63, v63, v60
	v_min_f32_e32 v46, v24, v22
	v_max_f32_e32 v24, v24, v22
	v_min_f32_e32 v139, v138, v148
	v_max_f32_e32 v138, v138, v148
	v_min_f32_e32 v141, v17, v50
	v_max_f32_e32 v17, v17, v50
	v_min_f32_e32 v140, v17, v139
	v_max_f32_e32 v17, v17, v139
	v_min_f32_e32 v136, v15, v23
	v_max_f32_e32 v15, v15, v23
	v_min_f32_e32 v5, v45, v46
	v_max_f32_e32 v45, v45, v46
	v_min_f32_e32 v143, v45, v136
	v_max_f32_e32 v45, v45, v136
	v_min_f32_e32 v145, v15, v17
	v_max_f32_e32 v15, v15, v17
	v_min_f32_e32 v144, v45, v140
	v_max_f32_e32 v45, v45, v140
	v_min_f32_e32 v9, v143, v141
	v_max_f32_e32 v143, v143, v141
	v_min_f32_e32 v4, v137, v61
	v_max_f32_e32 v137, v137, v61
	v_min_f32_e32 v142, v19, v24
	v_max_f32_e32 v19, v19, v24
	v_min_f32_e32 v12, v19, v4
	v_max_f32_e32 v19, v19, v4
	v_min_f32_e32 v3, v6, v63
	v_max_f32_e32 v6, v6, v63
	v_min_f32_e32 v8, v16, v62
	v_max_f32_e32 v16, v16, v62
	v_min_f32_e32 v7, v16, v3
	v_max_f32_e32 v16, v16, v3
	v_min_f32_e32 v26, v6, v19
	v_max_f32_e32 v6, v6, v19
	v_min_f32_e32 v134, v16, v12
	v_max_f32_e32 v16, v16, v12
	v_min_f32_e32 v10, v7, v142
	v_max_f32_e32 v7, v7, v142
	v_min_f32_e32 v11, v137, v15
	v_max_f32_e32 v137, v137, v15
	v_min_f32_e32 v149, v6, v145
	v_max_f32_e32 v6, v6, v145
	v_min_f32_e32 v151, v26, v45
	v_max_f32_e32 v26, v26, v45
	v_min_f32_e32 v150, v16, v144
	v_max_f32_e32 v16, v16, v144
	v_min_f32_e32 v20, v134, v143
	v_max_f32_e32 v134, v134, v143
	v_min_f32_e32 v21, v7, v9
	v_max_f32_e32 v7, v7, v9
	v_min_f32_e32 v153, v10, v5
	v_max_f32_e32 v10, v10, v5
	v_min_f32_e32 v155, v156, v157
	v_max_f32_e32 v156, v156, v157
	v_min_f32_e32 v154, v158, v159
	v_max_f32_e32 v158, v158, v159
	v_min_f32_e32 v2, v156, v158
	v_max_f32_e32 v156, v156, v158
	v_min_f32_e32 v13, v155, v154
	v_max_f32_e32 v155, v155, v154
; DI void phase_peer_q(const Params& p, int layer, u16* lds, const int WAVE_S) {
;     ...
;     for (int i = 0; i < 16; ++i)
; #pragma unroll
;       for (int j = 0; j < 16; ++j)
;         if ((i + 1) * (j + 1) <= 16) {
;           const float sv = t0[i] + t[j];
;           ins16(c, __uint_as_float((__float_as_uint(sv) & ~255u) | (uint32_t)(i * 16 + j)));
;         }
	v_min_f32_e32 v152, v155, v2
	v_max_f32_e32 v155, v155, v2
	v_min_f32_e32 v59, v160, v161
	v_max_f32_e32 v160, v160, v161
	v_min_f32_e32 v53, v162, v163
	v_max_f32_e32 v162, v162, v163
	v_min_f32_e32 v51, v160, v162
	v_max_f32_e32 v160, v160, v162
	v_min_f32_e32 v54, v59, v53
	v_max_f32_e32 v59, v59, v53
	v_min_f32_e32 v25, v59, v51
	v_max_f32_e32 v59, v59, v51
	v_min_f32_e32 v14, v156, v160
	v_max_f32_e32 v156, v156, v160
	v_min_f32_e32 v60, v152, v25
	v_max_f32_e32 v152, v152, v25
	v_min_f32_e32 v22, v152, v14
	v_max_f32_e32 v152, v152, v14
	v_min_f32_e32 v148, v155, v59
	v_max_f32_e32 v155, v155, v59
	v_min_f32_e32 v50, v13, v54
	v_max_f32_e32 v13, v13, v54
	v_min_f32_e32 v139, v13, v148
	v_max_f32_e32 v13, v13, v148
	v_min_f32_e32 v23, v155, v152
	v_max_f32_e32 v155, v155, v152
	v_min_f32_e32 v46, v13, v22
	v_max_f32_e32 v13, v13, v22
	v_min_f32_e32 v136, v139, v60
	v_max_f32_e32 v139, v139, v60
	v_min_f32_e32 v17, v34, v35
	v_max_f32_e32 v34, v34, v35
	v_min_f32_e32 v140, v36, v37
	v_max_f32_e32 v36, v36, v37
	v_min_f32_e32 v141, v34, v36
	v_max_f32_e32 v34, v34, v36
	v_min_f32_e32 v61, v17, v140
	v_max_f32_e32 v17, v17, v140
	v_min_f32_e32 v24, v17, v141
	v_max_f32_e32 v17, v17, v141
	v_min_f32_e32 v4, v38, v39
	v_max_f32_e32 v38, v38, v39
	v_min_f32_e32 v63, v40, v41
	v_max_f32_e32 v40, v40, v41
	v_min_f32_e32 v62, v38, v40
	v_max_f32_e32 v38, v38, v40
	v_min_f32_e32 v3, v4, v63
	v_max_f32_e32 v4, v4, v63
	v_min_f32_e32 v19, v4, v62
	v_max_f32_e32 v4, v4, v62
	v_min_f32_e32 v12, v34, v38
	v_max_f32_e32 v34, v34, v38
	v_min_f32_e32 v142, v24, v19
	v_max_f32_e32 v24, v24, v19
	v_min_f32_e32 v15, v24, v12
	v_max_f32_e32 v24, v24, v12
	v_min_f32_e32 v145, v17, v4
	v_max_f32_e32 v17, v17, v4
	v_min_f32_e32 v45, v61, v3
	v_max_f32_e32 v61, v61, v3
	v_min_f32_e32 v144, v61, v145
	v_max_f32_e32 v61, v61, v145
	v_min_f32_e32 v143, v17, v24
	v_max_f32_e32 v17, v17, v24
	v_min_f32_e32 v9, v61, v15
	v_max_f32_e32 v61, v61, v15
	v_min_f32_e32 v5, v144, v142
	v_max_f32_e32 v144, v144, v142
	v_min_f32_e32 v157, v156, v34
	v_max_f32_e32 v156, v156, v34
	v_min_f32_e32 v159, v46, v9
	v_max_f32_e32 v46, v46, v9
	v_min_f32_e32 v158, v46, v157
	v_max_f32_e32 v46, v46, v157
	v_min_f32_e32 v154, v23, v143
	v_max_f32_e32 v23, v23, v143
	v_min_f32_e32 v2, v136, v5
	v_max_f32_e32 v136, v136, v5
	v_min_f32_e32 v161, v136, v154
	v_max_f32_e32 v136, v136, v154
	v_min_f32_e32 v163, v23, v46
	v_max_f32_e32 v23, v23, v46
	v_min_f32_e32 v162, v136, v158
	v_max_f32_e32 v136, v136, v158
	v_min_f32_e32 v53, v161, v159
	v_max_f32_e32 v161, v161, v159
	v_min_f32_e32 v51, v155, v17
	v_max_f32_e32 v155, v155, v17
	v_min_f32_e32 v160, v139, v144
	v_max_f32_e32 v139, v139, v144
	v_min_f32_e32 v25, v139, v51
	v_max_f32_e32 v139, v139, v51
	v_min_f32_e32 v14, v13, v61
	v_max_f32_e32 v13, v13, v61
	v_min_f32_e32 v59, v50, v45
	v_max_f32_e32 v50, v50, v45
	v_min_f32_e32 v54, v50, v14
	v_max_f32_e32 v50, v50, v14
	v_min_f32_e32 v148, v13, v139
	v_max_f32_e32 v13, v13, v139
	v_min_f32_e32 v152, v50, v25
	v_max_f32_e32 v50, v50, v25
	v_min_f32_e32 v22, v54, v160
	v_max_f32_e32 v54, v54, v160
	v_min_f32_e32 v60, v155, v23
	v_max_f32_e32 v155, v155, v23
	v_min_f32_e32 v35, v13, v163
	v_max_f32_e32 v13, v13, v163
	v_min_f32_e32 v37, v148, v136
	v_max_f32_e32 v148, v148, v136
	v_min_f32_e32 v36, v50, v162
	v_max_f32_e32 v50, v50, v162
	v_min_f32_e32 v140, v152, v161
	v_max_f32_e32 v152, v152, v161
	v_min_f32_e32 v141, v54, v53
	v_max_f32_e32 v54, v54, v53
	v_min_f32_e32 v39, v22, v2
	v_max_f32_e32 v22, v22, v2
	v_max_f32_e32 v18, v18, v8
	v_max_f32_e32 v44, v44, v153
	v_max_f32_e32 v55, v55, v10
	v_max_f32_e32 v47, v47, v21
	v_max_f32_e32 v27, v27, v7
	v_max_f32_e32 v57, v57, v20
	v_max_f32_e32 v29, v29, v134
	v_max_f32_e32 v58, v58, v150
	v_max_f32_e32 v28, v28, v16
	v_max_f32_e32 v48, v48, v151
	v_max_f32_e32 v64, v64, v26
	v_max_f32_e32 v52, v52, v149
	v_max_f32_e32 v65, v65, v6
	v_max_f32_e32 v56, v56, v11
	v_max_f32_e32 v135, v135, v137
	v_max_f32_e32 v49, v49, v138
	v_min_f32_e32 v41, v18, v28
	v_max_f32_e32 v18, v18, v28
	v_min_f32_e32 v40, v44, v48
	v_max_f32_e32 v44, v44, v48
	v_min_f32_e32 v63, v55, v64
	v_max_f32_e32 v55, v55, v64
	v_min_f32_e32 v62, v47, v52
	v_max_f32_e32 v47, v47, v52
	v_min_f32_e32 v38, v27, v65
	v_max_f32_e32 v27, v27, v65
	v_min_f32_e32 v19, v57, v56
	v_max_f32_e32 v57, v57, v56
	v_min_f32_e32 v12, v29, v135
	v_max_f32_e32 v29, v29, v135
	v_min_f32_e32 v4, v58, v49
	v_max_f32_e32 v58, v58, v49
	v_min_f32_e32 v3, v18, v27
	v_max_f32_e32 v18, v18, v27
	v_min_f32_e32 v145, v44, v57
	v_max_f32_e32 v44, v44, v57
	v_min_f32_e32 v24, v55, v29
	v_max_f32_e32 v55, v55, v29
	v_min_f32_e32 v15, v47, v58
	v_max_f32_e32 v47, v47, v58
	v_min_f32_e32 v142, v41, v38
	v_max_f32_e32 v41, v41, v38
	v_min_f32_e32 v34, v40, v19
	v_max_f32_e32 v40, v40, v19
	v_min_f32_e32 v9, v63, v12
	v_max_f32_e32 v63, v63, v12
	v_min_f32_e32 v157, v62, v4
	v_max_f32_e32 v62, v62, v4
	v_min_f32_e32 v143, v18, v55
	v_max_f32_e32 v18, v18, v55
	v_min_f32_e32 v5, v44, v47
	v_max_f32_e32 v44, v44, v47
	v_min_f32_e32 v154, v3, v24
	v_max_f32_e32 v3, v3, v24
	v_min_f32_e32 v46, v145, v15
	v_max_f32_e32 v145, v145, v15
	v_min_f32_e32 v158, v41, v63
	v_max_f32_e32 v41, v41, v63
	v_min_f32_e32 v159, v40, v62
	v_max_f32_e32 v40, v40, v62
	v_min_f32_e32 v17, v142, v9
	v_max_f32_e32 v142, v142, v9
	v_min_f32_e32 v144, v34, v157
	v_max_f32_e32 v34, v34, v157
	v_min_f32_e32 v51, v18, v44
	v_max_f32_e32 v18, v18, v44
	v_min_f32_e32 v61, v143, v5
	v_max_f32_e32 v143, v143, v5
	v_min_f32_e32 v45, v3, v145
	v_max_f32_e32 v3, v3, v145
	v_min_f32_e32 v14, v154, v46
	v_max_f32_e32 v154, v154, v46
; DI void phase_peer_q(const Params& p, int layer, u16* lds, const int WAVE_S) {
;     ...
;     for (int i = 0; i < 16; ++i)
; #pragma unroll
;       for (int j = 0; j < 16; ++j)
;         if ((i + 1) * (j + 1) <= 16) {
;           const float sv = t0[i] + t[j];
;           ins16(c, __uint_as_float((__float_as_uint(sv) & ~255u) | (uint32_t)(i * 16 + j)));
;         }
;     __syncthreads();
;     uint32_t* wl = (uint32_t*)lds + wave * (32 * 33);
;     if (h == 0) {
; #pragma unroll
;       for (int i = 0; i < 16; ++i) { wl[r * 33 + i] = __float_as_uint(t0[i]); wl[r * 33 + 16 + i] = __float_as_uint(t[i]); }
;     }
;     float sv[16];
;     uint32_t ev[16];
;     float smax = -3.0e38f;
; #pragma unroll
;     for (int k = 0; k < 16; ++k) {
;       const uint32_t pos = __float_as_uint(c[k]) & 255u;
;       const uint32_t ai = wl[r * 33 + (pos >> 4)];
;       const uint32_t bj = wl[r * 33 + 16 + (pos & 15)];
	v_min_f32_e32 v139, v41, v40
	v_max_f32_e32 v41, v41, v40
	v_min_f32_e32 v25, v158, v159
	v_max_f32_e32 v158, v158, v159
	v_min_f32_e32 v160, v142, v34
	v_max_f32_e32 v142, v142, v34
	v_min_f32_e32 v23, v17, v144
	v_max_f32_e32 v17, v17, v144
	v_max_f32_e32 v18, v18, v59
	v_max_f32_e32 v51, v51, v39
	v_max_f32_e32 v143, v143, v22
	v_max_f32_e32 v61, v61, v141
	v_max_f32_e32 v3, v3, v54
	v_max_f32_e32 v45, v45, v140
	v_max_f32_e32 v154, v154, v152
	v_max_f32_e32 v14, v14, v36
	v_max_f32_e32 v41, v41, v50
	v_max_f32_e32 v139, v139, v37
	v_max_f32_e32 v158, v158, v148
	v_max_f32_e32 v25, v25, v35
	v_max_f32_e32 v142, v142, v13
	v_max_f32_e32 v160, v160, v60
	v_max_f32_e32 v17, v17, v155
	v_max_f32_e32 v23, v23, v156
	v_min_f32_e32 v163, v18, v41
	v_max_f32_e32 v18, v18, v41
	v_min_f32_e32 v136, v51, v139
	v_max_f32_e32 v51, v51, v139
	v_min_f32_e32 v162, v143, v158
	v_max_f32_e32 v143, v143, v158
	v_min_f32_e32 v161, v61, v25
	v_max_f32_e32 v61, v61, v25
	v_min_f32_e32 v53, v3, v142
	v_max_f32_e32 v3, v3, v142
	v_min_f32_e32 v2, v45, v160
	v_max_f32_e32 v45, v45, v160
	v_min_f32_e32 v138, v154, v17
	v_max_f32_e32 v154, v154, v17
	v_min_f32_e32 v137, v14, v23
	v_max_f32_e32 v14, v14, v23
	v_min_f32_e32 v11, v18, v3
	v_max_f32_e32 v18, v18, v3
	v_min_f32_e32 v6, v51, v45
	v_max_f32_e32 v51, v51, v45
	v_min_f32_e32 v149, v143, v154
	v_max_f32_e32 v143, v143, v154
	v_min_f32_e32 v26, v61, v14
	v_max_f32_e32 v61, v61, v14
	v_min_f32_e32 v151, v163, v53
	v_max_f32_e32 v163, v163, v53
	v_min_f32_e32 v16, v136, v2
	v_max_f32_e32 v136, v136, v2
	v_min_f32_e32 v150, v162, v138
	v_max_f32_e32 v162, v162, v138
	v_min_f32_e32 v134, v161, v137
	v_max_f32_e32 v161, v161, v137
	v_min_f32_e32 v20, v18, v143
	v_max_f32_e32 v18, v18, v143
	v_min_f32_e32 v7, v51, v61
	v_max_f32_e32 v51, v51, v61
	v_min_f32_e32 v21, v11, v149
	v_max_f32_e32 v11, v11, v149
	v_min_f32_e32 v10, v6, v26
	v_max_f32_e32 v6, v6, v26
	v_min_f32_e32 v153, v163, v162
	v_max_f32_e32 v163, v163, v162
	v_min_f32_e32 v8, v136, v161
	v_max_f32_e32 v136, v136, v161
	v_min_f32_e32 v28, v151, v150
	v_max_f32_e32 v151, v151, v150
	v_min_f32_e32 v48, v16, v134
	v_max_f32_e32 v16, v16, v134
	v_min_f32_e32 v64, v18, v51
	v_max_f32_e32 v18, v18, v51
	v_min_f32_e32 v52, v20, v7
	v_max_f32_e32 v20, v20, v7
	v_min_f32_e32 v65, v11, v6
	v_max_f32_e32 v11, v11, v6
	v_min_f32_e32 v56, v21, v10
	v_max_f32_e32 v21, v21, v10
	v_min_f32_e32 v135, v163, v136
	v_max_f32_e32 v163, v163, v136
	v_min_f32_e32 v49, v153, v8
	v_max_f32_e32 v153, v153, v8
	v_min_f32_e32 v27, v151, v16
	v_max_f32_e32 v151, v151, v16
	v_min_f32_e32 v57, v28, v48
	v_max_f32_e32 v28, v28, v48
	v_med3_f32 v57, v28, v57, v42
	v_med3_f32 v28, v27, v28, v42
	v_med3_f32 v27, v151, v27, v42
	v_med3_f32 v151, v49, v151, v42
	v_med3_f32 v49, v153, v49, v42
	v_med3_f32 v153, v135, v153, v42
	v_med3_f32 v135, v163, v135, v42
	v_med3_f32 v163, v56, v163, v42
	v_med3_f32 v56, v21, v56, v42
	v_med3_f32 v21, v65, v21, v42
	v_med3_f32 v65, v11, v65, v42
	v_med3_f32 v11, v52, v11, v42
	v_med3_f32 v52, v20, v52, v42
	v_med3_f32 v20, v64, v20, v42
	v_med3_f32 v64, v18, v64, v42
	v_max_f32_e32 v18, v18, v42
	v_med3_f32 v57, v28, v57, v43
	v_med3_f32 v28, v27, v28, v43
	v_med3_f32 v27, v151, v27, v43
	v_med3_f32 v151, v49, v151, v43
	v_med3_f32 v49, v153, v49, v43
	v_med3_f32 v153, v135, v153, v43
	v_med3_f32 v135, v163, v135, v43
	v_med3_f32 v163, v56, v163, v43
	v_med3_f32 v56, v21, v56, v43
	v_med3_f32 v21, v65, v21, v43
	v_med3_f32 v65, v11, v65, v43
	v_med3_f32 v11, v52, v11, v43
	v_med3_f32 v52, v20, v52, v43
	v_med3_f32 v20, v64, v20, v43
	v_med3_f32 v64, v18, v64, v43
	v_max_f32_e32 v18, v18, v43
	v_mov_b32_e32 v0, v18
	v_mov_b32_e32 v6, v64
	v_mov_b32_e32 v5, v20
	v_mov_b32_e32 v4, v52
	v_mov_b32_e32 v14, v11
	v_mov_b32_e32 v13, v65
	v_mov_b32_e32 v12, v21
	v_mov_b32_e32 v11, v56
	v_mov_b32_e32 v22, v163
	v_mov_b32_e32 v21, v135
	v_mov_b32_e32 v20, v153
	v_mov_b32_e32 v19, v49
	v_mov_b32_e32 v29, v151
	v_mov_b32_e32 v3, v57
	v_mov_b32_e32 v58, v27
	v_mov_b32_e32 v27, v28
	v_mov_b32_e32 v28, v58
	v_and_b32_e32 v2, 15, v0
	v_lshrrev_b32_e32 v0, 4, v0
	v_and_b32_e32 v0, 15, v0
	v_lshl_add_u32 v8, v0, 2, v124
	v_and_b32_e32 v0, 15, v6
	v_lshrrev_b32_e32 v7, 4, v6
	v_lshl_add_u32 v6, v0, 2, v124
	v_and_b32_e32 v0, 15, v5
	v_lshl_add_u32 v9, v0, 2, v124
	v_lshrrev_b32_e32 v0, 4, v4
	v_lshrrev_b32_e32 v5, 4, v5
	v_and_b32_e32 v7, 15, v7
	v_and_b32_e32 v0, 15, v0
	v_and_b32_e32 v5, 15, v5
	v_lshl_add_u32 v2, v2, 2, v124
	v_lshl_add_u32 v7, v7, 2, v124
	v_lshl_add_u32 v10, v5, 2, v124
	v_lshl_add_u32 v15, v0, 2, v124
	v_and_b32_e32 v0, 15, v4
	v_lshl_add_u32 v16, v0, 2, v124
	ds_read_b32 v0, v2 offset:64
	ds_read_b32 v4, v8
	ds_read_b32 v5, v7
	ds_read_b32 v6, v6 offset:64
	ds_read_b32 v7, v9 offset:64
	ds_read_b32 v8, v10
	ds_read_b32 v9, v15
	ds_read_b32 v10, v16 offset:64
	v_lshrrev_b32_e32 v15, 4, v13
	v_and_b32_e32 v13, 15, v13
	v_lshl_add_u32 v16, v13, 2, v124
	v_and_b32_e32 v13, 15, v12
	v_and_b32_e32 v2, 15, v14
	v_lshrrev_b32_e32 v14, 4, v14
	v_lshl_add_u32 v17, v13, 2, v124
	v_lshrrev_b32_e32 v13, 4, v11
	v_lshrrev_b32_e32 v12, 4, v12
	v_and_b32_e32 v15, 15, v15
	v_and_b32_e32 v14, 15, v14
	v_and_b32_e32 v13, 15, v13
	v_and_b32_e32 v12, 15, v12
	v_lshl_add_u32 v2, v2, 2, v124
	v_lshl_add_u32 v14, v14, 2, v124
	v_lshl_add_u32 v15, v15, 2, v124
	v_lshl_add_u32 v18, v12, 2, v124
	v_lshl_add_u32 v23, v13, 2, v124
	v_and_b32_e32 v11, 15, v11
	v_lshl_add_u32 v24, v11, 2, v124
	ds_read_b32 v11, v2 offset:64
	ds_read_b32 v12, v14
	ds_read_b32 v13, v15
	ds_read_b32 v14, v16 offset:64
	ds_read_b32 v15, v17 offset:64
	ds_read_b32 v16, v18
	ds_read_b32 v17, v23
; #define tid_opaque() tid_from(WAVE_S)
; DI void phase_peer_q(const Params& p, int layer, u16* lds, const int WAVE_S) {
;     ...
;     for (int k = 0; k < 16; ++k) {
;       const uint32_t pos = __float_as_uint(c[k]) & 255u;
;       const uint32_t ai = wl[r * 33 + (pos >> 4)];
;       const uint32_t bj = wl[r * 33 + 16 + (pos & 15)];
;       sv[k] = __uint_as_float(ai & ~127u) + __uint_as_float(bj & ~127u);
;       ev[k] = ((ai & 127u) << 7) | (bj & 127u);
;       smax = fmaxf(smax, sv[k]);
;     }
;     float ssum = 0.f;
; #pragma unroll
;     for (int k = 0; k < 16; ++k) { sv[k] = __expf(sv[k] - smax); ssum += sv[k]; }
;     const float rinv = 1.f / ssum;
;     const int tq = tid_opaque();
;     const size_t item = (size_t)(tt * 128 + (tq >> 6) * 32 + (tq & 31)) * 8 + head;
;     if (((tq >> 5) & 1) == 0) {
	ds_read_b32 v18, v24 offset:64
	v_lshrrev_b32_e32 v23, 4, v21
	v_and_b32_e32 v21, 15, v21
	v_lshl_add_u32 v24, v21, 2, v124
	v_and_b32_e32 v21, 15, v20
	v_and_b32_e32 v2, 15, v22
	v_lshrrev_b32_e32 v22, 4, v22
	v_lshl_add_u32 v25, v21, 2, v124
	v_lshrrev_b32_e32 v21, 4, v19
	v_lshrrev_b32_e32 v20, 4, v20
	v_and_b32_e32 v23, 15, v23
	v_and_b32_e32 v22, 15, v22
	v_and_b32_e32 v21, 15, v21
	v_and_b32_e32 v20, 15, v20
	v_lshl_add_u32 v2, v2, 2, v124
	v_lshl_add_u32 v22, v22, 2, v124
	v_lshl_add_u32 v23, v23, 2, v124
	v_lshl_add_u32 v26, v20, 2, v124
	v_lshl_add_u32 v30, v21, 2, v124
	v_and_b32_e32 v19, 15, v19
	v_lshl_add_u32 v31, v19, 2, v124
	ds_read_b32 v19, v2 offset:64
	ds_read_b32 v20, v22
	ds_read_b32 v21, v23
	ds_read_b32 v22, v24 offset:64
	ds_read_b32 v23, v25 offset:64
	ds_read_b32 v24, v26
	ds_read_b32 v25, v30
	ds_read_b32 v26, v31 offset:64
	v_lshrrev_b32_e32 v30, 4, v28
	v_and_b32_e32 v28, 15, v28
	v_lshl_add_u32 v31, v28, 2, v124
	v_and_b32_e32 v28, 15, v27
	v_and_b32_e32 v2, 15, v29
	v_lshrrev_b32_e32 v29, 4, v29
	v_lshl_add_u32 v32, v28, 2, v124
	v_lshrrev_b32_e32 v28, 4, v3
	v_lshrrev_b32_e32 v27, 4, v27
	v_and_b32_e32 v30, 15, v30
	v_and_b32_e32 v29, 15, v29
	v_and_b32_e32 v28, 15, v28
	v_and_b32_e32 v27, 15, v27
	v_lshl_add_u32 v2, v2, 2, v124
	v_lshl_add_u32 v29, v29, 2, v124
	v_lshl_add_u32 v30, v30, 2, v124
	v_lshl_add_u32 v33, v27, 2, v124
	v_lshl_add_u32 v34, v28, 2, v124
	v_and_b32_e32 v3, 15, v3
	v_lshl_add_u32 v3, v3, 2, v124
	ds_read_b32 v27, v2 offset:64
	ds_read_b32 v28, v29
	ds_read_b32 v29, v30
	ds_read_b32 v30, v31 offset:64
	ds_read_b32 v31, v32 offset:64
	ds_read_b32 v32, v33
	ds_read_b32 v33, v34
	ds_read_b32 v34, v3 offset:64
	v_mbcnt_lo_u32_b32 v35, -1, 0
	v_mbcnt_hi_u32_b32 v35, -1, v35
	s_nop 0
	v_add_u32_e32 v2, s33, v35
	v_ashrrev_i32_e32 v2, 1, v2
	v_and_b32_e32 v2, 0xffffffe0, v2
	v_lshl_add_u32 v2, s40, 7, v2
	v_and_or_b32 v2, v35, 31, v2
	v_ashrrev_i32_e32 v3, 31, v2
	v_lshlrev_b64 v[2:3], 3, v[2:3]
	v_and_b32_e32 v35, 32, v35
	v_or_b32_e32 v2, s98, v2
	v_cmp_ne_u32_e32 vcc, 0, v35
	s_and_saveexec_b64 s[18:19], vcc
	s_xor_b64 s[40:41], exec, s[18:19]
	s_cbranch_execz .LBB0_398
;   DI u16* sel_e() const { return (u16*)(ws + OFF_sel_e); }
;   DI float* sel_g() const { return (float*)(ws + OFF_sel_g); }
; #define tid_opaque() tid_from(WAVE_S)
; DI void phase_peer_q(const Params& p, int layer, u16* lds, const int WAVE_S) {
;     ...
;       sv[k] = __uint_as_float(ai & ~127u) + __uint_as_float(bj & ~127u);
;       ev[k] = ((ai & 127u) << 7) | (bj & 127u);
;       smax = fmaxf(smax, sv[k]);
;     }
;     float ssum = 0.f;
; #pragma unroll
;     for (int k = 0; k < 16; ++k) { sv[k] = __expf(sv[k] - smax); ssum += sv[k]; }
;     const float rinv = 1.f / ssum;
;     const int tq = tid_opaque();
;     const size_t item = (size_t)(tt * 128 + (tq >> 6) * 32 + (tq & 31)) * 8 + head;
;     if (((tq >> 5) & 1) == 0) {
;       u32x4* de = (u32x4*)(p.sel_e() + item * 16);
; #pragma unroll
;       for (int g4 = 0; g4 < 2; ++g4) {
;         u32x4 w;
; #pragma unroll
;         for (int j = 0; j < 4; ++j) w[j] = ev[8 * g4 + 2 * j] | (ev[8 * g4 + 2 * j + 1] << 16);
;         de[g4] = w;
;       }
;     } else {
;       f32x4* dg = (f32x4*)(p.sel_g() + item * 16);
; #pragma unroll
;       for (int g4 = 0; g4 < 4; ++g4) {
;         f32x4 w = {sv[4 * g4] * rinv, sv[4 * g4 + 1] * rinv, sv[4 * g4 + 2] * rinv, sv[4 * g4 + 3] * rinv};
;         dg[g4] = w;
;       }
	s_waitcnt lgkmcnt(14)
	v_and_b32_e32 v0, 0xffffff80, v0
	v_and_b32_e32 v4, 0xffffff80, v4
	v_add_f32_e32 v0, v0, v4
	v_and_b32_e32 v4, 0xffffff80, v6
	v_and_b32_e32 v6, 0xffffff80, v7
	v_and_b32_e32 v7, 0xffffff80, v8
	v_add_f32_e32 v8, v6, v7
	v_and_b32_e32 v6, 0xffffff80, v10
	v_and_b32_e32 v7, 0xffffff80, v9
	v_add_f32_e32 v9, v6, v7
	v_and_b32_e32 v6, 0xffffff80, v11
	v_and_b32_e32 v7, 0xffffff80, v12
	v_add_f32_e32 v10, v6, v7
	v_and_b32_e32 v6, 0xffffff80, v14
	v_and_b32_e32 v7, 0xffffff80, v13
	v_add_f32_e32 v11, v6, v7
	v_and_b32_e32 v6, 0xffffff80, v15
	v_and_b32_e32 v7, 0xffffff80, v16
	v_add_f32_e32 v12, v6, v7
	v_and_b32_e32 v6, 0xffffff80, v18
	v_and_b32_e32 v7, 0xffffff80, v17
	v_and_b32_e32 v5, 0xffffff80, v5
	v_add_f32_e32 v13, v6, v7
	v_and_b32_e32 v6, 0xffffff80, v19
	v_and_b32_e32 v7, 0xffffff80, v20
	v_add_f32_e32 v4, v4, v5
	v_add_f32_e32 v14, v6, v7
	s_waitcnt lgkmcnt(12)
	v_and_b32_e32 v6, 0xffffff80, v22
	v_and_b32_e32 v7, 0xffffff80, v21
	v_max3_f32 v5, v0, s92, v4
	v_add_f32_e32 v15, v6, v7
	s_waitcnt lgkmcnt(11)
	v_and_b32_e32 v6, 0xffffff80, v23
	s_waitcnt lgkmcnt(10)
	v_and_b32_e32 v7, 0xffffff80, v24
	v_max3_f32 v5, v5, v8, v9
	v_add_f32_e32 v16, v6, v7
	s_waitcnt lgkmcnt(8)
	v_and_b32_e32 v6, 0xffffff80, v26
	v_and_b32_e32 v7, 0xffffff80, v25
	v_max3_f32 v5, v5, v10, v11
	v_add_f32_e32 v17, v6, v7
	s_waitcnt lgkmcnt(7)
	v_and_b32_e32 v6, 0xffffff80, v27
	s_waitcnt lgkmcnt(6)
	v_and_b32_e32 v7, 0xffffff80, v28
	v_max3_f32 v5, v5, v12, v13
	v_add_f32_e32 v18, v6, v7
	s_waitcnt lgkmcnt(4)
	v_and_b32_e32 v6, 0xffffff80, v30
	v_and_b32_e32 v7, 0xffffff80, v29
	v_max3_f32 v5, v5, v14, v15
	v_add_f32_e32 v19, v6, v7
	s_waitcnt lgkmcnt(3)
	v_and_b32_e32 v6, 0xffffff80, v31
	s_waitcnt lgkmcnt(2)
	v_and_b32_e32 v7, 0xffffff80, v32
	v_max3_f32 v5, v5, v16, v17
	v_add_f32_e32 v20, v6, v7
	s_waitcnt lgkmcnt(0)
	v_and_b32_e32 v6, 0xffffff80, v34
	v_and_b32_e32 v7, 0xffffff80, v33
	v_max3_f32 v5, v5, v18, v19
	v_add_f32_e32 v21, v6, v7
	v_max3_f32 v22, v5, v20, v21
	v_sub_f32_e32 v0, v0, v22
	v_mul_f32_e32 v0, 0x3fb8aa3b, v0
	v_exp_f32_e32 v6, v0
	v_sub_f32_e32 v0, v4, v22
	v_mul_f32_e32 v0, 0x3fb8aa3b, v0
	v_exp_f32_e32 v7, v0
	v_sub_f32_e32 v0, v8, v22
	v_mul_f32_e32 v0, 0x3fb8aa3b, v0
	v_exp_f32_e32 v4, v0
	v_sub_f32_e32 v0, v9, v22
	v_mul_f32_e32 v0, 0x3fb8aa3b, v0
	v_sub_f32_e32 v8, v10, v22
	v_exp_f32_e32 v5, v0
	v_mul_f32_e32 v8, 0x3fb8aa3b, v8
	v_sub_f32_e32 v9, v11, v22
	v_add_f32_e32 v0, 0, v6
	v_exp_f32_e32 v8, v8
	v_mul_f32_e32 v9, 0x3fb8aa3b, v9
	v_sub_f32_e32 v10, v12, v22
	v_add_f32_e32 v0, v7, v0
	v_exp_f32_e32 v9, v9
	v_mul_f32_e32 v10, 0x3fb8aa3b, v10
	v_sub_f32_e32 v11, v13, v22
	v_add_f32_e32 v0, v4, v0
	v_exp_f32_e32 v10, v10
	v_mul_f32_e32 v11, 0x3fb8aa3b, v11
	v_sub_f32_e32 v12, v14, v22
	v_add_f32_e32 v0, v5, v0
	v_exp_f32_e32 v11, v11
	v_mul_f32_e32 v12, 0x3fb8aa3b, v12
	v_sub_f32_e32 v13, v15, v22
	v_add_f32_e32 v0, v8, v0
	v_exp_f32_e32 v12, v12
	v_mul_f32_e32 v13, 0x3fb8aa3b, v13
	v_sub_f32_e32 v14, v16, v22
	v_add_f32_e32 v0, v9, v0
	v_exp_f32_e32 v13, v13
	v_mul_f32_e32 v14, 0x3fb8aa3b, v14
	v_sub_f32_e32 v15, v17, v22
	v_add_f32_e32 v0, v10, v0
	v_exp_f32_e32 v14, v14
	v_mul_f32_e32 v15, 0x3fb8aa3b, v15
	v_sub_f32_e32 v16, v18, v22
	v_add_f32_e32 v0, v11, v0
	v_exp_f32_e32 v15, v15
	v_mul_f32_e32 v16, 0x3fb8aa3b, v16
	v_sub_f32_e32 v17, v19, v22
	v_add_f32_e32 v0, v12, v0
	v_exp_f32_e32 v16, v16
	v_mul_f32_e32 v17, 0x3fb8aa3b, v17
	v_sub_f32_e32 v18, v20, v22
	v_add_f32_e32 v0, v13, v0
	v_exp_f32_e32 v17, v17
	v_mul_f32_e32 v18, 0x3fb8aa3b, v18
	v_sub_f32_e32 v19, v21, v22
	v_add_f32_e32 v0, v14, v0
	v_exp_f32_e32 v18, v18
	v_mul_f32_e32 v19, 0x3fb8aa3b, v19
	v_add_f32_e32 v0, v15, v0
	v_exp_f32_e32 v19, v19
	v_add_f32_e32 v0, v16, v0
	v_add_f32_e32 v0, v17, v0
	v_add_f32_e32 v0, v18, v0
	v_add_f32_e32 v0, v19, v0
	v_div_scale_f32 v20, s[18:19], v0, v0, 1.0
	v_rcp_f32_e32 v21, v20
	v_readlane_b32 s18, v166, 0
	v_lshlrev_b64 v[2:3], 6, v[2:3]
	v_readlane_b32 s19, v166, 1
	v_fma_f32 v22, -v20, v21, 1.0
	v_fmac_f32_e32 v21, v22, v21
	v_div_scale_f32 v22, vcc, 1.0, v0, 1.0
	v_mul_f32_e32 v23, v22, v21
	v_fma_f32 v24, -v20, v23, v22
	v_fmac_f32_e32 v23, v24, v21
	v_fma_f32 v20, -v20, v23, v22
	v_div_fmas_f32 v20, v20, v21, v23
	v_div_fixup_f32 v0, v20, v0, 1.0
	v_lshl_add_u64 v[20:21], s[18:19], 0, v[2:3]
	v_pk_mul_f32 v[4:5], v[4:5], v[0:1] op_sel_hi:[1,0]
	v_pk_mul_f32 v[2:3], v[6:7], v[0:1] op_sel_hi:[1,0]
	global_store_dwordx4 v[20:21], v[2:5], off
	s_nop 1
	v_pk_mul_f32 v[4:5], v[10:11], v[0:1] op_sel_hi:[1,0]
	v_pk_mul_f32 v[2:3], v[8:9], v[0:1] op_sel_hi:[1,0]
	global_store_dwordx4 v[20:21], v[2:5], off offset:16
	s_nop 1
	v_pk_mul_f32 v[4:5], v[14:15], v[0:1] op_sel_hi:[1,0]
	v_pk_mul_f32 v[2:3], v[12:13], v[0:1] op_sel_hi:[1,0]
	global_store_dwordx4 v[20:21], v[2:5], off offset:32
	s_nop 1
	v_pk_mul_f32 v[4:5], v[18:19], v[0:1] op_sel_hi:[1,0]
	v_pk_mul_f32 v[2:3], v[16:17], v[0:1] op_sel_hi:[1,0]
	global_store_dwordx4 v[20:21], v[2:5], off offset:48
